# gdn_sample conv batched + state prefetch; gla_sample gate-weight loads hoisted; scan touch-prefetch
# speedup vs baseline: 1.0587x; 1.0089x over previous
.LBB0_1003:
	s_or_b64 exec, exec, s[0:1]
	s_and_b32 s0, s4, -4
	s_add_i32 s5, s5, s0
	v_bfe_u32 v6, v0, 6, 1
	s_ashr_i32 s0, s5, 5
	v_and_b32_e32 v22, 15, v0
	s_ashr_i32 s1, s0, 31
	v_lshlrev_b32_e32 v24, 4, v6
	v_bfe_u32 v1, v0, 4, 2
	s_and_b32 s9, s4, 3
	s_ashr_i32 s6, s5, 2
	s_lshl_b64 s[4:5], s[0:1], 23
	v_or_b32_e32 v7, v24, v22
	s_movk_i32 s1, 0x110
	v_ashrrev_i32_e32 v17, 7, v0
	v_lshlrev_b32_e32 v25, 4, v1
	v_mad_u32_u24 v8, v7, s1, 0
	v_lshlrev_b32_e32 v7, 7, v7
	v_lshlrev_b32_e32 v14, 8, v6
	v_add_u32_e32 v26, v8, v25
	v_sub_u32_e32 v27, v8, v7
	v_lshlrev_b32_e32 v7, 5, v17
	v_lshlrev_b32_e32 v23, 2, v1
	v_lshlrev_b32_e32 v1, 3, v1
	v_lshlrev_b32_e32 v6, 5, v6
	v_lshlrev_b32_e32 v8, 1, v22
	v_add3_u32 v28, v27, v7, v1
	v_lshl_or_b32 v7, v17, 4, v23
	v_add3_u32 v18, 0, v6, v8
	s_movk_i32 s1, 0x50
	v_ashrrev_i32_e32 v6, 2, v0
	v_lshlrev_b32_e32 v10, 4, v0
	s_and_b32 s3, s6, 7
	s_lshl_b32 s2, s9, 5
	s_ashr_i32 s7, s6, 31
	v_mul_lo_u32 v19, v7, s1
	v_sub_u32_e32 v20, v26, v1
	v_mul_lo_u32 v1, v6, s1
	v_and_b32_e32 v7, 48, v10
	v_add3_u32 v29, 0, v1, v7
	s_add_u32 s4, s4, 0xc500000
	v_ashrrev_i32_e32 v7, 31, v6
	s_addc_u32 s5, s5, 0
	v_lshlrev_b64 v[6:7], 12, v[6:7]
	v_lshl_add_u64 v[8:9], s[4:5], 0, v[6:7]
	v_and_b32_e32 v0, 3, v0
	s_lshl_b32 s1, s9, 6
	s_lshl_b32 s4, s3, 8
	v_lshlrev_b32_e32 v2, 11, v17
	v_lshlrev_b32_e32 v0, 4, v0
	s_or_b32 s1, s4, s1
	s_lshl_b64 s[36:37], s[6:7], 14
	v_and_b32_e32 v6, 0x3f0, v10
	v_ashrrev_i32_e32 v3, 31, v2
	v_lshlrev_b32_e32 v4, 10, v17
	v_or3_b32 v8, v8, v0, s1
	v_or_b32_e32 v0, s36, v6
	v_mov_b32_e32 v1, s37
	s_lshl_b64 s[36:37], s[6:7], 13
	v_ashrrev_i32_e32 v5, 31, v4
	v_lshl_add_u64 v[10:11], v[2:3], 1, v[0:1]
	v_or_b32_e32 v0, s36, v6
	v_mov_b32_e32 v1, s37
	v_lshlrev_b32_e32 v16, 6, v17
	v_lshl_add_u64 v[12:13], v[4:5], 1, v[0:1]
	v_lshl_or_b32 v0, s9, 9, v14
	v_add_u32_e32 v0, v0, v16
	v_or3_b32 v0, v0, v25, v22
	v_lshlrev_b32_e32 v0, 2, v0
	s_lshl_b64 s[4:5], s[6:7], 2
	s_lshl_b64 s[6:7], s[6:7], 15
	v_ashrrev_i32_e32 v1, 31, v0
	v_mov_b32_e32 v4, 0
	v_lshl_add_u64 v[14:15], v[0:1], 2, s[6:7]
	s_mov_b32 s1, -2
	v_add_u32_e32 v30, v18, v19
	v_add_u32_e32 v31, v20, v16
	v_mov_b32_e32 v5, v4
	v_mov_b32_e32 v6, v4
	v_mov_b32_e32 v7, v4
	v_mov_b32_e32 v0, v4
	v_mov_b32_e32 v1, v4
	v_mov_b32_e32 v2, v4
	v_mov_b32_e32 v3, v4
	s_waitcnt vmcnt(0) lgkmcnt(0)
	s_barrier
	v_mov_b32_e32 v140, 0
	v_mov_b32_e32 v142, 0
	s_movk_i32 s32, 0x0
	v_cmp_le_u32_e32 vcc, s32, v180
	v_subrev_u32_e32 v141, s32, v180
	v_lshlrev_b32_e32 v141, 7, v141
	s_lshr_b32 s101, s6, 15
	s_mul_i32 s100, s101, 0x4000
	s_add_u32 s100, s100, 0x1a000000
	v_add_u32_e32 v141, s100, v141
	v_cndmask_b32_e32 v140, v140, v141, vcc
	v_mov_b32_e32 v141, 0x100000
	v_cndmask_b32_e32 v142, v142, v141, vcc
	s_movk_i32 s32, 0x80
	v_cmp_le_u32_e32 vcc, s32, v180
	v_subrev_u32_e32 v141, s32, v180
	v_lshlrev_b32_e32 v141, 7, v141
	s_lshr_b32 s101, s6, 15
	s_mul_i32 s100, s101, 0x4000
	s_add_u32 s100, s100, 0x19000000
	v_add_u32_e32 v141, s100, v141
	v_cndmask_b32_e32 v140, v140, v141, vcc
	v_mov_b32_e32 v141, 0x100000
	v_cndmask_b32_e32 v142, v142, v141, vcc
	s_movk_i32 s32, 0x100
	v_cmp_le_u32_e32 vcc, s32, v180
	v_subrev_u32_e32 v141, s32, v180
	v_lshlrev_b32_e32 v141, 7, v141
	s_lshr_b32 s101, s6, 15
	s_mul_i32 s100, s101, 0x4000
	s_add_u32 s100, s100, 0x1b000000
	v_add_u32_e32 v141, s100, v141
	v_cndmask_b32_e32 v140, v140, v141, vcc
	v_mov_b32_e32 v141, 0x100000
	v_cndmask_b32_e32 v142, v142, v141, vcc
	s_movk_i32 s32, 0x180
	v_cmp_le_u32_e32 vcc, s32, v180
	v_subrev_u32_e32 v141, s32, v180
	v_lshlrev_b32_e32 v141, 7, v141
	s_lshr_b32 s101, s6, 15
	s_mul_i32 s100, s101, 0x2000
	s_add_u32 s100, s100, 0x1c000000
	v_add_u32_e32 v141, s100, v141
	v_cndmask_b32_e32 v140, v140, v141, vcc
	v_mov_b32_e32 v141, 0x80000
	v_cndmask_b32_e32 v142, v142, v141, vcc
	s_movk_i32 s32, 0x1c0
	v_cmp_le_u32_e32 vcc, s32, v180
	v_subrev_u32_e32 v141, s32, v180
	v_lshlrev_b32_e32 v141, 7, v141
	s_lshr_b32 s101, s6, 15
	s_mul_i32 s100, s101, 0x8000
	s_add_u32 s100, s100, 0x1c800000
	s_lshl_b32 s101, s9, 13
	s_add_u32 s100, s100, s101
	v_add_u32_e32 v141, s100, v141
	v_cndmask_b32_e32 v140, v140, v141, vcc
	v_mov_b32_e32 v141, 0x200000
	v_cndmask_b32_e32 v142, v142, v141, vcc
	v_lshrrev_b32_e32 v141, 1, v142
	v_mul_lo_u32 v143, v141, 4
	v_add_u32_e32 v140, v140, v143
	v_add_u32_e32 v141, v140, v141
.LBB0_1004:
	s_nop 0
	v_lshl_add_u64 v[18:19], s[12:13], 0, v[10:11]
	v_add_co_u32_e32 v60, vcc, 0x1a000000, v18
	ds_read_b128 v[32:35], v26
	ds_read_b128 v[36:39], v26 offset:64
	ds_read_b128 v[40:43], v26 offset:128
	ds_read_b128 v[44:47], v26 offset:192
	v_addc_co_u32_e32 v61, vcc, 0, v19, vcc
	v_add_co_u32_e32 v76, vcc, 0x19000000, v18
	flat_load_dwordx4 v[48:51], v[60:61]
	flat_load_dwordx4 v[52:55], v[60:61] offset:1024
	flat_load_dwordx4 v[56:59], v[60:61] offset:2048
	s_nop 0
	flat_load_dwordx4 v[60:63], v[60:61] offset:3072
	v_addc_co_u32_e32 v77, vcc, 0, v19, vcc
	flat_load_dwordx4 v[64:67], v[76:77]
	flat_load_dwordx4 v[68:71], v[76:77] offset:1024
	flat_load_dwordx4 v[72:75], v[76:77] offset:2048
	s_nop 0
	flat_load_dwordx4 v[76:79], v[76:77] offset:3072
	v_lshl_add_u64 v[136:137], s[12:13], 0, v[12:13]
	v_add_co_u32_e32 v84, vcc, 0x1c000000, v136
	v_lshl_add_u64 v[20:21], s[12:13], 0, v[14:15]
	s_nop 0
	v_addc_co_u32_e32 v85, vcc, 0, v137, vcc
	v_add_co_u32_e32 v100, vcc, 0x1b000000, v18
	flat_load_dwordx4 v[80:83], v[84:85]
	s_nop 0
	flat_load_dwordx4 v[84:87], v[84:85] offset:1024
	v_addc_co_u32_e32 v101, vcc, 0, v19, vcc
	v_add_co_u32_e32 v104, vcc, 0x1c800000, v20
	flat_load_dwordx4 v[88:91], v[100:101]
	flat_load_dwordx4 v[92:95], v[100:101] offset:1024
	flat_load_dwordx4 v[96:99], v[100:101] offset:2048
	s_nop 0
	flat_load_dwordx4 v[100:103], v[100:101] offset:3072
	v_addc_co_u32_e32 v105, vcc, 0, v21, vcc
	flat_load_dwordx4 v[104:107], v[104:105]
	s_add_u32 s6, s12, s4
	s_addc_u32 s7, s13, s5
	v_mov_b32_e32 v16, s6
	v_mov_b32_e32 v109, s7
	v_add_co_u32_e32 v108, vcc, 0x20c00000, v16
	v_add_u32_e32 v139, v27, v25
	s_nop 0
	v_addc_co_u32_e32 v109, vcc, 0, v109, vcc
	flat_load_dword v138, v[108:109]
	flat_load_dword v16, v[108:109] offset:128
	v_add_co_u32_e32 v120, vcc, 0x1a080000, v18
	s_add_i32 s1, s1, 2
	s_nop 0
	v_addc_co_u32_e32 v121, vcc, 0, v19, vcc
	v_add_co_u32_e32 v132, vcc, 0x19080000, v18
	flat_load_dwordx4 v[108:111], v[120:121]
	flat_load_dwordx4 v[112:115], v[120:121] offset:1024
	flat_load_dwordx4 v[116:119], v[120:121] offset:2048
	s_nop 0
	flat_load_dwordx4 v[120:123], v[120:121] offset:3072
	v_addc_co_u32_e32 v133, vcc, 0, v19, vcc
	flat_load_dwordx4 v[124:127], v[132:133]
	v_add_co_u32_e32 v136, vcc, 0x1c040000, v136
	s_add_u32 s4, s4, 0x100
	s_nop 0
	v_addc_co_u32_e32 v137, vcc, 0, v137, vcc
	v_add_co_u32_e32 v18, vcc, 0x1b080000, v18
	s_addc_u32 s5, s5, 0
	s_nop 0
	v_addc_co_u32_e32 v19, vcc, 0, v19, vcc
	v_add_co_u32_e32 v20, vcc, 0x1c900000, v20
	v_lshl_add_u64 v[10:11], v[10:11], 0, s[96:97]
	s_nop 0
	v_addc_co_u32_e32 v21, vcc, 0, v21, vcc
	v_lshl_add_u64 v[12:13], v[12:13], 0, s[92:93]
	v_lshl_add_u64 v[14:15], v[14:15], 0, s[10:11]
	s_cmp_lt_u32 s1, 30
	s_waitcnt vmcnt(0) lgkmcnt(0)
	v_mfma_f32_16x16x32_bf16 v[48:51], v[48:51], v[32:35], 0
	v_mul_f32_e64 v6, v6, v138
	v_mul_f32_e64 v7, v7, v138
	v_mfma_f32_16x16x32_bf16 v[32:35], v[64:67], v[32:35], 0
	flat_load_dwordx4 v[64:67], v[132:133] offset:1024
	flat_load_dwordx4 v[128:131], v[132:133] offset:2048
	s_nop 0
	flat_load_dwordx4 v[132:135], v[132:133] offset:3072
	v_pk_mul_f32 v[4:5], v[4:5], v[138:139] op_sel_hi:[1,0]
	v_pk_mul_f32 v[2:3], v[2:3], v[138:139] op_sel_hi:[1,0]
	v_mfma_f32_16x16x32_bf16 v[48:51], v[52:55], v[36:39], v[48:51]
	v_mul_f32_e64 v0, v0, v138
	v_mul_f32_e64 v1, v1, v138
	v_mfma_f32_16x16x32_bf16 v[32:35], v[68:71], v[36:39], v[32:35]
	flat_load_dwordx4 v[36:39], v[136:137]
	flat_load_dwordx4 v[52:55], v[136:137] offset:1024
	v_mfma_f32_16x16x32_bf16 v[48:51], v[56:59], v[40:43], v[48:51]
	flat_load_dwordx4 v[56:59], v[18:19]
	v_mfma_f32_16x16x32_bf16 v[32:35], v[72:75], v[40:43], v[32:35]
	flat_load_dwordx4 v[40:43], v[18:19] offset:1024
	flat_load_dwordx4 v[68:71], v[18:19] offset:2048
	flat_load_dwordx4 v[72:75], v[18:19] offset:3072
	s_nop 0
	flat_load_dwordx4 v[18:21], v[20:21]
	v_mfma_f32_16x16x32_bf16 v[32:35], v[76:79], v[44:47], v[32:35]
	v_mfma_f32_16x16x32_bf16 v[48:51], v[60:63], v[44:47], v[48:51]
	s_nop 6
	v_sub_f32_e32 v34, v106, v34
	v_sub_f32_e32 v35, v107, v35
	v_sub_f32_e32 v32, v104, v32
	v_sub_f32_e32 v33, v105, v33
	v_add_u32_e32 v33, 0x8000, v33
	v_add_u32_e32 v32, 0x8000, v32
	v_add_u32_e32 v35, 0x8000, v35
	v_add_u32_e32 v34, 0x8000, v34
	v_perm_b32 v32, v33, v32, s81
	v_perm_b32 v33, v35, v34, s81
	ds_write_b64 v28, v[32:33] offset:8704
	s_waitcnt lgkmcnt(0)
	s_barrier
	ds_read_b128 v[32:35], v139 offset:8704
	ds_read_b128 v[44:47], v139 offset:8768
	s_waitcnt lgkmcnt(0)
	v_mfma_f32_16x16x32_bf16 v[48:51], v[80:83], v[32:35], v[48:51]
	v_mfma_f32_16x16x32_bf16 v[4:7], v[88:91], v[32:35], v[4:7]
	v_mfma_f32_16x16x32_bf16 v[0:3], v[96:99], v[32:35], v[0:3]
	v_mfma_f32_16x16x32_bf16 v[32:35], v[84:87], v[44:47], v[48:51]
	v_mfma_f32_16x16x32_bf16 v[4:7], v[92:95], v[44:47], v[4:7]
	v_mfma_f32_16x16x32_bf16 v[0:3], v[100:103], v[44:47], v[0:3]
	s_nop 5
	v_add_u32_e32 v32, 0x8000, v32
	v_add_u32_e32 v33, 0x8000, v33
	v_add_u32_e32 v34, 0x8000, v34
	v_add_u32_e32 v35, 0x8000, v35
	v_add_u32_e32 v44, 0x8000, v5
	v_add_u32_e32 v45, 0x8000, v4
	v_add_u32_e32 v46, 0x8000, v7
	v_add_u32_e32 v47, 0x8000, v6
	v_add_u32_e32 v48, 0x8000, v1
	v_add_u32_e32 v49, 0x8000, v0
	v_add_u32_e32 v50, 0x8000, v3
	v_add_u32_e32 v51, 0x8000, v2
	ds_write_b16_d16_hi v30, v32 offset:13312
	ds_write_b16_d16_hi v30, v33 offset:13392
	ds_write_b16_d16_hi v30, v34 offset:13472
	ds_write_b16_d16_hi v30, v35 offset:13552
	v_perm_b32 v32, v44, v45, s81
	v_perm_b32 v33, v46, v47, s81
	v_perm_b32 v34, v48, v49, s81
	v_perm_b32 v35, v50, v51, s81
	ds_write2_b64 v31, v[32:33], v[34:35] offset1:4
	s_waitcnt lgkmcnt(0)
	s_barrier
	ds_read_b128 v[32:35], v26
	ds_read_b128 v[44:47], v26 offset:64
	s_waitcnt lgkmcnt(0)
	v_mfma_f32_16x16x32_bf16 v[48:51], v[124:127], v[32:35], 0
	v_mul_f32_e64 v6, v16, v6
	v_mul_f32_e64 v7, v16, v7
	v_pk_mul_f32 v[4:5], v[16:17], v[4:5] op_sel_hi:[0,1]
	v_pk_mul_f32 v[2:3], v[16:17], v[2:3] op_sel_hi:[0,1]
	v_mfma_f32_16x16x32_bf16 v[32:35], v[108:111], v[32:35], 0
	v_mul_f32_e64 v0, v16, v0
	v_mul_f32_e64 v1, v16, v1
	s_waitcnt vmcnt(0)
	global_load_dword v143, v140, s[12:13]
	global_load_dword v247, v141, s[12:13]
	v_add_u32_e32 v140, v140, v142
	v_add_u32_e32 v141, v141, v142
	v_mfma_f32_16x16x32_bf16 v[48:51], v[64:67], v[44:47], v[48:51]
	v_mfma_f32_16x16x32_bf16 v[32:35], v[112:115], v[44:47], v[32:35]
	ds_read_b128 v[44:47], v26 offset:128
	ds_read_b128 v[60:63], v26 offset:192
	s_waitcnt lgkmcnt(1)
	v_mfma_f32_16x16x32_bf16 v[48:51], v[128:131], v[44:47], v[48:51]
	v_mfma_f32_16x16x32_bf16 v[32:35], v[116:119], v[44:47], v[32:35]
	s_waitcnt lgkmcnt(0)
	v_mfma_f32_16x16x32_bf16 v[44:47], v[132:135], v[60:63], v[48:51]
	v_mfma_f32_16x16x32_bf16 v[32:35], v[120:123], v[60:63], v[32:35]
	s_nop 6
	v_sub_f32_e32 v20, v20, v46
	v_sub_f32_e32 v21, v21, v47
	v_sub_f32_e32 v18, v18, v44
	v_sub_f32_e32 v19, v19, v45
	v_add_u32_e32 v19, 0x8000, v19
	v_add_u32_e32 v18, 0x8000, v18
	v_add_u32_e32 v21, 0x8000, v21
	v_add_u32_e32 v20, 0x8000, v20
	v_perm_b32 v18, v19, v18, s81
	v_perm_b32 v19, v21, v20, s81
	ds_write_b64 v28, v[18:19] offset:8704
	s_waitcnt lgkmcnt(0)
	s_barrier
	ds_read_b128 v[18:21], v139 offset:8704
	ds_read_b128 v[44:47], v139 offset:8768
	s_waitcnt lgkmcnt(1)
	v_mfma_f32_16x16x32_bf16 v[32:35], v[36:39], v[18:21], v[32:35]
	v_mfma_f32_16x16x32_bf16 v[4:7], v[56:59], v[18:21], v[4:7]
	v_mfma_f32_16x16x32_bf16 v[0:3], v[68:71], v[18:21], v[0:3]
	s_waitcnt lgkmcnt(0)
	v_mfma_f32_16x16x32_bf16 v[18:21], v[52:55], v[44:47], v[32:35]
	v_mfma_f32_16x16x32_bf16 v[4:7], v[40:43], v[44:47], v[4:7]
	s_nop 2
	v_lshl_add_u64 v[32:33], s[12:13], 0, v[8:9]
	s_nop 2
	v_add_u32_e32 v16, 0x8000, v18
	v_add_u32_e32 v18, 0x8000, v19
	v_mfma_f32_16x16x32_bf16 v[0:3], v[72:75], v[44:47], v[0:3]
	v_add_u32_e32 v19, 0x8000, v20
	v_add_u32_e32 v20, 0x8000, v21
	v_add_u32_e32 v21, 0x8000, v5
	v_add_u32_e32 v34, 0x8000, v4
	v_add_u32_e32 v35, 0x8000, v7
	v_add_u32_e32 v36, 0x8000, v6
	s_nop 1
	v_add_u32_e32 v37, 0x8000, v1
	v_add_u32_e32 v38, 0x8000, v0
	v_add_u32_e32 v39, 0x8000, v3
	v_add_u32_e32 v40, 0x8000, v2
	ds_write_b16_d16_hi v30, v16 offset:18432
	ds_write_b16_d16_hi v30, v18 offset:18512
	ds_write_b16_d16_hi v30, v19 offset:18592
	ds_write_b16_d16_hi v30, v20 offset:18672
	v_perm_b32 v18, v21, v34, s81
	v_perm_b32 v19, v35, v36, s81
	v_perm_b32 v20, v37, v38, s81
	v_perm_b32 v21, v39, v40, s81
	ds_write2_b64 v31, v[18:19], v[20:21] offset1:4
	s_waitcnt lgkmcnt(0)
	s_barrier
	ds_read_b128 v[18:21], v29 offset:13312
	v_lshl_add_u64 v[8:9], v[8:9], 0, s[92:93]
	s_waitcnt lgkmcnt(0)
	flat_store_dwordx4 v[32:33], v[18:21]
	s_cbranch_scc1 .LBB0_1004
	s_lshl_b32 s0, s0, 3
	s_add_i32 s0, s0, s8
	s_or_b32 s0, s0, s3
	s_ashr_i32 s1, s0, 31
	s_lshl_b64 s[0:1], s[0:1], 16
	s_add_u32 s0, s40, s0
	s_addc_u32 s1, s41, s1
	s_lshl_b32 s2, s2, 2
	s_add_u32 s0, s0, s2
	s_addc_u32 s1, s1, 0
	v_lshlrev_b32_e32 v144, 2, v24
	v_lshl_add_u64 v[8:9], s[0:1], 0, v[144:145]
	v_lshlrev_b32_e32 v144, 2, v22
	v_lshl_or_b32 v10, v17, 5, v23
	v_lshl_add_u64 v[8:9], v[8:9], 0, v[144:145]
	s_mov_b64 s[0:1], 0x4800000
	v_ashrrev_i32_e32 v11, 31, v10
	v_lshl_add_u64 v[8:9], v[8:9], 0, s[0:1]
	v_lshlrev_b64 v[12:13], 9, v[10:11]
	v_lshl_add_u64 v[12:13], v[8:9], 0, v[12:13]
	flat_store_dword v[12:13], v4
	v_or_b32_e32 v12, 1, v10
	v_ashrrev_i32_e32 v13, 31, v12
	v_lshlrev_b64 v[12:13], 9, v[12:13]
	v_lshl_add_u64 v[12:13], v[8:9], 0, v[12:13]
	v_or_b32_e32 v4, 2, v10
	flat_store_dword v[12:13], v5
	v_ashrrev_i32_e32 v5, 31, v4
	v_lshlrev_b64 v[4:5], 9, v[4:5]
	v_lshl_add_u64 v[4:5], v[8:9], 0, v[4:5]
	flat_store_dword v[4:5], v6
	v_or_b32_e32 v4, 3, v10
	v_ashrrev_i32_e32 v5, 31, v4
	v_lshlrev_b64 v[4:5], 9, v[4:5]
	v_lshl_add_u64 v[4:5], v[8:9], 0, v[4:5]
	flat_store_dword v[4:5], v7
	v_or_b32_e32 v4, 16, v10
	v_ashrrev_i32_e32 v5, 31, v4
	v_lshlrev_b64 v[4:5], 9, v[4:5]
	v_lshl_add_u64 v[4:5], v[8:9], 0, v[4:5]
	flat_store_dword v[4:5], v0
	v_or_b32_e32 v4, 17, v10
	v_ashrrev_i32_e32 v5, 31, v4
	v_lshlrev_b64 v[4:5], 9, v[4:5]
	v_lshl_add_u64 v[4:5], v[8:9], 0, v[4:5]
	v_or_b32_e32 v0, 18, v10
	flat_store_dword v[4:5], v1
	v_ashrrev_i32_e32 v1, 31, v0
	v_lshlrev_b64 v[0:1], 9, v[0:1]
	v_lshl_add_u64 v[0:1], v[8:9], 0, v[0:1]
	flat_store_dword v[0:1], v2
	v_or_b32_e32 v0, 19, v10
	v_ashrrev_i32_e32 v1, 31, v0
	v_lshlrev_b64 v[0:1], 9, v[0:1]
	v_lshl_add_u64 v[0:1], v[8:9], 0, v[0:1]
	flat_store_dword v[0:1], v3
	s_waitcnt lgkmcnt(0)
	s_barrier

.LBB0_1030:
	s_or_b64 exec, exec, s[2:3]
	s_waitcnt vmcnt(0) lgkmcnt(0)
	s_barrier
	s_and_saveexec_b64 s[4:5], s[36:37]
	s_cbranch_execz .LBB0_1033
	s_lshl_b32 s2, s74, 7
	s_or_b32 s6, s2, s21
	s_lshl_b32 s2, s74, 9
	v_and_b32_e32 v2, 0x7f, v16
	s_add_u32 s2, s19, s2
	v_or_b32_e32 v144, s6, v2
	s_addc_u32 s3, s20, 0
	v_lshl_add_u64 v[0:1], v[144:145], 2, s[54:55]
	v_lshlrev_b32_e32 v144, 2, v2
	v_lshl_add_u64 v[2:3], s[2:3], 0, v[144:145]
	v_lshl_add_u64 v[2:3], v[2:3], 0, s[22:23]
	s_mov_b64 s[2:3], 0x1000
	v_lshl_add_u64 v[4:5], v[2:3], 0, s[2:3]
	s_mov_b64 s[2:3], 0x1800
	v_lshl_add_u64 v[6:7], v[2:3], 0, s[2:3]
	s_mov_b64 s[2:3], 0x2000
	v_lshl_add_u64 v[8:9], v[2:3], 0, s[2:3]
	s_mov_b64 s[2:3], 0x2800
	v_lshl_add_u64 v[10:11], v[2:3], 0, s[2:3]
	s_mov_b64 s[2:3], 0x3000
	v_lshl_add_u64 v[12:13], v[2:3], 0, s[2:3]
	s_mov_b64 s[2:3], 0x3800
	v_lshl_add_u64 v[14:15], v[2:3], 0, s[2:3]
	s_mov_b64 s[2:3], 0x4800
	v_lshl_add_u64 v[20:21], v[2:3], 0, s[2:3]
	s_mov_b64 s[2:3], 0x5000
	v_lshl_add_u64 v[22:23], v[2:3], 0, s[2:3]
	s_mov_b64 s[2:3], 0x5800
	v_lshl_add_u64 v[24:25], v[2:3], 0, s[2:3]
	s_mov_b64 s[2:3], 0x6000
	v_lshl_add_u64 v[26:27], v[2:3], 0, s[2:3]
	s_mov_b64 s[2:3], 0x6800
	v_lshl_add_u64 v[28:29], v[2:3], 0, s[2:3]
	s_mov_b64 s[2:3], 0x7000
	v_lshl_add_u64 v[30:31], v[2:3], 0, s[2:3]
	s_mov_b64 s[2:3], 0x7800
	v_lshl_add_u64 v[32:33], v[2:3], 0, s[2:3]
	s_add_i32 s2, 0, 0x2000
	v_lshl_add_u64 v[18:19], v[2:3], 0, s[78:79]
	v_lshl_add_u32 v17, v16, 2, s2
	s_mov_b64 s[36:37], 0
	v_mov_b32_e32 v34, v16
	global_load_dword v122, v[0:1], off
	global_load_dword v123, v[2:3], off
	global_load_dword v124, v[2:3], off offset:2048
	global_load_dword v125, v[4:5], off
	global_load_dword v126, v[6:7], off
	global_load_dword v127, v[8:9], off
	global_load_dword v128, v[10:11], off
	global_load_dword v129, v[12:13], off
	global_load_dword v130, v[14:15], off
	global_load_dword v131, v[18:19], off
	global_load_dword v132, v[20:21], off
	global_load_dword v133, v[22:23], off
	global_load_dword v134, v[24:25], off
	global_load_dword v135, v[26:27], off
	global_load_dword v136, v[28:29], off
	global_load_dword v137, v[30:31], off
	global_load_dword v138, v[32:33], off
	s_waitcnt vmcnt(0)
.LBB0_1032:
	v_ashrrev_i32_e32 v36, 3, v34
	v_lshlrev_b32_e32 v36, 2, v36
	v_and_b32_e32 v36, 0xffffffc0, v36
	v_add_u32_e32 v48, 0, v36
	v_mov_b32_e32 v35, v122
	ds_read_b128 v[36:39], v48 offset:45056
	ds_read_b128 v[40:43], v48 offset:45072
	ds_read_b128 v[44:47], v48 offset:45088
	ds_read_b128 v[48:51], v48 offset:45104
	v_mov_b32_e32 v52, v123
	v_cmp_lt_i32_e32 vcc, s58, v34
	s_or_b64 s[36:37], vcc, s[36:37]
	s_waitcnt lgkmcnt(0)
	v_fmac_f32_e32 v35, v36, v52
	v_mov_b32_e32 v36, v124
	v_fmac_f32_e32 v35, v37, v36
	v_mov_b32_e32 v36, v125
	v_fmac_f32_e32 v35, v38, v36
	v_mov_b32_e32 v36, v126
	v_fmac_f32_e32 v35, v39, v36
	v_mov_b32_e32 v36, v127
	v_fmac_f32_e32 v35, v40, v36
	v_mov_b32_e32 v36, v128
	v_fmac_f32_e32 v35, v41, v36
	v_mov_b32_e32 v36, v129
	v_fmac_f32_e32 v35, v42, v36
	v_mov_b32_e32 v36, v130
	v_fmac_f32_e32 v35, v43, v36
	v_mov_b32_e32 v36, v131
	v_mov_b32_e32 v37, v132
	v_pk_mul_f32 v[36:37], v[44:45], v[36:37]
	s_nop 0
	v_add_f32_e32 v35, v35, v36
	v_add_f32_e32 v35, v35, v37
	v_mov_b32_e32 v36, v133
	v_mov_b32_e32 v37, v134
	v_pk_mul_f32 v[36:37], v[46:47], v[36:37]
	s_nop 0
	v_add_f32_e32 v35, v35, v36
	v_add_f32_e32 v35, v35, v37
	v_mov_b32_e32 v36, v135
	v_mov_b32_e32 v37, v136
	v_pk_mul_f32 v[36:37], v[48:49], v[36:37]
	s_nop 0
	v_add_f32_e32 v35, v35, v36
	v_add_f32_e32 v35, v35, v37
	v_mov_b32_e32 v36, v137
	v_mov_b32_e32 v37, v138
	v_pk_mul_f32 v[36:37], v[50:51], v[36:37]
	s_nop 0
	v_add_f32_e32 v35, v35, v36
	v_add_f32_e32 v35, v35, v37
	v_min_f32_e32 v36, 0, v35
	v_mul_f32_e64 v35, |v35|, s56
	v_exp_f32_e32 v35, v35
	s_nop 0
	v_add_f32_e32 v35, 1.0, v35
	v_log_f32_e32 v35, v35
	s_nop 0
	v_fmac_f32_e32 v36, 0xbf317218, v35
	v_mul_f32_e32 v35, 0x3d800000, v36
	v_mul_f32_e32 v35, 0x3fb8aa3b, v35
	v_exp_f32_e32 v35, v35
	ds_write_b32 v17, v35
	v_add_u32_e32 v35, 0x200, v34
	v_add_u32_e32 v17, 0x800, v17
	v_mov_b32_e32 v34, v35
	s_andn2_b64 exec, exec, s[36:37]
	s_cbranch_execnz .LBB0_1032

.LBB0_1050:
	s_and_b32 s0, s84, -8
	s_and_b32 s6, s84, 7
	s_ashr_i32 s7, s84, 3
	s_ashr_i32 s1, s0, 31
	v_mov_b32_e32 v64, v180
	s_add_u32 s36, s0, 0x2000
	s_addc_u32 s37, s1, 0
	s_add_i32 s2, s7, s24
	s_lshl_b32 s3, s2, 3
	s_or_b32 s3, s3, s6
	s_lshl_b32 s3, s3, 16
	s_add_u32 s100, s28, s3
	s_addc_u32 s101, s29, 0
	v_lshrrev_b32_e32 v48, 7, v64
	v_lshlrev_b32_e32 v48, 14, v48
	v_and_b32_e32 v49, 0x7f, v64
	v_lshl_or_b32 v48, v49, 2, v48
	v_add_u32_e32 v49, 0x1000, v48
	v_add_u32_e32 v50, 0x2000, v48
	v_add_u32_e32 v51, 0x3000, v48
	s_mov_b32 s4, 0x2aaaaaab
	v_mul_hi_i32 v76, v64, s4
	v_lshrrev_b32_e32 v76, 3, v76
	v_mul_lo_u32 v77, v76, 48
	v_sub_u32_e32 v77, v64, v77
	v_lshrrev_b32_e32 v78, 4, v77
	v_and_b32_e32 v52, 15, v77
	s_lshl_b32 s4, s6, 7
	v_lshlrev_b32_e32 v79, 10, v78
	v_lshl_or_b32 v79, v52, 3, v79
	v_or_b32_e32 v79, s4, v79
	v_lshlrev_b32_e32 v80, 2, v79
	v_lshlrev_b32_e32 v53, 12, v78
	v_lshl_add_u32 v53, v76, 9, v53
	v_lshl_add_u32 v53, v52, 5, v53
	v_add_u32_e32 v54, -3, v76
	v_max_i32_e32 v54, 0, v54
	v_add_u32_e32 v54, s36, v54
	v_mul_lo_u32 v54, v54, s86
	v_lshl_add_u32 v54, v79, 1, v54
	v_add_u32_e32 v55, -2, v76
	v_max_i32_e32 v55, 0, v55
	v_add_u32_e32 v55, s36, v55
	v_mul_lo_u32 v55, v55, s86
	v_lshl_add_u32 v55, v79, 1, v55
	v_add_u32_e32 v56, -1, v76
	v_max_i32_e32 v56, 0, v56
	v_add_u32_e32 v56, s36, v56
	v_mul_lo_u32 v56, v56, s86
	v_lshl_add_u32 v56, v79, 1, v56
	v_add_u32_e32 v57, s36, v76
	v_mul_lo_u32 v57, v57, s86
	v_lshl_add_u32 v57, v79, 1, v57
	s_mul_i32 s5, s2, 3
	v_add_u32_e32 v58, 0, v76
	v_min_u32_e32 v58, 2, v58
	v_add_u32_e32 v58, s5, v58
	v_mul_lo_u32 v58, v58, s71
	v_add_u32_e32 v58, v58, v80
	v_add_u32_e32 v59, 1, v76
	v_min_u32_e32 v59, 2, v59
	v_add_u32_e32 v59, s5, v59
	v_mul_lo_u32 v59, v59, s71
	v_add_u32_e32 v59, v59, v80
	v_add_u32_e32 v60, 2, v76
	v_min_u32_e32 v60, 2, v60
	v_add_u32_e32 v60, s5, v60
	v_mul_lo_u32 v60, v60, s71
	v_add_u32_e32 v60, v60, v80
	s_add_i32 s4, s5, -5
	v_add_u32_e32 v61, s4, v76
	v_mul_lo_u32 v61, v61, s71
	v_add_u32_e32 v61, v61, v80
	s_movk_i32 s4, 0x180
	v_cmp_gt_u32_e32 vcc, s4, v64
	s_and_saveexec_b64 s[0:1], vcc
	s_mov_b64 s[2:3], exec
	global_load_dwordx4 v[84:87], v80, s[14:15]
	global_load_dwordx4 v[88:91], v80, s[14:15] offset:16
	v_add_u32_e32 v62, 0x3000, v80
	global_load_dwordx4 v[92:95], v62, s[14:15]
	global_load_dwordx4 v[96:99], v62, s[14:15] offset:16
	v_add_u32_e32 v62, 0x6000, v80
	global_load_dwordx4 v[100:103], v62, s[14:15]
	global_load_dwordx4 v[104:107], v62, s[14:15] offset:16
	v_add_u32_e32 v62, 0x9000, v80
	global_load_dwordx4 v[108:111], v62, s[14:15]
	global_load_dwordx4 v[112:115], v62, s[14:15] offset:16
	global_load_dwordx4 v[116:119], v54, s[12:13]
	global_load_dwordx4 v[120:123], v55, s[12:13]
	global_load_dwordx4 v[124:127], v56, s[12:13]
	global_load_dwordx4 v[128:131], v57, s[12:13]
	global_load_dwordx4 v[132:135], v58, s[30:31]
	global_load_dwordx4 v[136:139], v58, s[30:31] offset:16
	global_load_dwordx4 v[140:143], v59, s[30:31]
	global_load_dwordx4 v[160:163], v59, s[30:31] offset:16
	global_load_dwordx4 v[164:167], v60, s[30:31]
	global_load_dwordx4 v[168:171], v60, s[30:31] offset:16
	s_mov_b64 exec, s[0:1]
	global_load_dword v190, v48, s[100:101] nt
	global_load_dword v191, v48, s[100:101] offset:512 nt
	global_load_dword v192, v48, s[100:101] offset:1024 nt
	global_load_dword v193, v48, s[100:101] offset:1536 nt
	global_load_dword v194, v48, s[100:101] offset:2048 nt
	global_load_dword v195, v48, s[100:101] offset:2560 nt
	global_load_dword v196, v48, s[100:101] offset:3072 nt
	global_load_dword v197, v48, s[100:101] offset:3584 nt
	global_load_dword v198, v49, s[100:101] nt
	global_load_dword v199, v49, s[100:101] offset:512 nt
	global_load_dword v200, v49, s[100:101] offset:1024 nt
	global_load_dword v201, v49, s[100:101] offset:1536 nt
	global_load_dword v202, v49, s[100:101] offset:2048 nt
	global_load_dword v203, v49, s[100:101] offset:2560 nt
	global_load_dword v204, v49, s[100:101] offset:3072 nt
	global_load_dword v205, v49, s[100:101] offset:3584 nt
	global_load_dword v206, v50, s[100:101] nt
	global_load_dword v207, v50, s[100:101] offset:512 nt
	global_load_dword v208, v50, s[100:101] offset:1024 nt
	global_load_dword v209, v50, s[100:101] offset:1536 nt
	global_load_dword v210, v50, s[100:101] offset:2048 nt
	global_load_dword v211, v50, s[100:101] offset:2560 nt
	global_load_dword v212, v50, s[100:101] offset:3072 nt
	global_load_dword v213, v50, s[100:101] offset:3584 nt
	global_load_dword v214, v51, s[100:101] nt
	global_load_dword v215, v51, s[100:101] offset:512 nt
	global_load_dword v216, v51, s[100:101] offset:1024 nt
	global_load_dword v217, v51, s[100:101] offset:1536 nt
	global_load_dword v218, v51, s[100:101] offset:2048 nt
	global_load_dword v219, v51, s[100:101] offset:2560 nt
	global_load_dword v220, v51, s[100:101] offset:3072 nt
	global_load_dword v221, v51, s[100:101] offset:3584 nt
	s_mov_b64 exec, s[2:3]
	s_cbranch_execz .Lgs_done
	s_waitcnt vmcnt(32)
	v_lshlrev_b32_e32 v0, 16, v116
	v_and_b32_e32 v1, 0xffff0000, v116
	v_lshlrev_b32_e32 v2, 16, v117
	v_and_b32_e32 v3, 0xffff0000, v117
	v_lshlrev_b32_e32 v4, 16, v118
	v_and_b32_e32 v5, 0xffff0000, v118
	v_lshlrev_b32_e32 v6, 16, v119
	v_and_b32_e32 v7, 0xffff0000, v119
	v_cmp_gt_u32_e32 vcc, 3, v76
	s_nop 1
	v_cndmask_b32_e32 v0, v0, v132, vcc
	v_cndmask_b32_e32 v1, v1, v133, vcc
	v_cndmask_b32_e32 v2, v2, v134, vcc
	v_cndmask_b32_e32 v3, v3, v135, vcc
	v_cndmask_b32_e32 v4, v4, v136, vcc
	v_cndmask_b32_e32 v5, v5, v137, vcc
	v_cndmask_b32_e32 v6, v6, v138, vcc
	v_cndmask_b32_e32 v7, v7, v139, vcc
	v_lshlrev_b32_e32 v8, 16, v120
	v_and_b32_e32 v9, 0xffff0000, v120
	v_lshlrev_b32_e32 v10, 16, v121
	v_and_b32_e32 v11, 0xffff0000, v121
	v_lshlrev_b32_e32 v12, 16, v122
	v_and_b32_e32 v13, 0xffff0000, v122
	v_lshlrev_b32_e32 v14, 16, v123
	v_and_b32_e32 v15, 0xffff0000, v123
	v_cmp_gt_u32_e32 vcc, 2, v76
	s_nop 1
	v_cndmask_b32_e32 v8, v8, v140, vcc
	v_cndmask_b32_e32 v9, v9, v141, vcc
	v_cndmask_b32_e32 v10, v10, v142, vcc
	v_cndmask_b32_e32 v11, v11, v143, vcc
	v_cndmask_b32_e32 v12, v12, v160, vcc
	v_cndmask_b32_e32 v13, v13, v161, vcc
	v_cndmask_b32_e32 v14, v14, v162, vcc
	v_cndmask_b32_e32 v15, v15, v163, vcc
	v_lshlrev_b32_e32 v16, 16, v124
	v_and_b32_e32 v17, 0xffff0000, v124
	v_lshlrev_b32_e32 v18, 16, v125
	v_and_b32_e32 v19, 0xffff0000, v125
	v_lshlrev_b32_e32 v20, 16, v126
	v_and_b32_e32 v21, 0xffff0000, v126
	v_lshlrev_b32_e32 v22, 16, v127
	v_and_b32_e32 v23, 0xffff0000, v127
	v_cmp_gt_u32_e32 vcc, 1, v76
	s_nop 1
	v_cndmask_b32_e32 v16, v16, v164, vcc
	v_cndmask_b32_e32 v17, v17, v165, vcc
	v_cndmask_b32_e32 v18, v18, v166, vcc
	v_cndmask_b32_e32 v19, v19, v167, vcc
	v_cndmask_b32_e32 v20, v20, v168, vcc
	v_cndmask_b32_e32 v21, v21, v169, vcc
	v_cndmask_b32_e32 v22, v22, v170, vcc
	v_cndmask_b32_e32 v23, v23, v171, vcc
	v_lshlrev_b32_e32 v24, 16, v128
	v_and_b32_e32 v25, 0xffff0000, v128
	v_lshlrev_b32_e32 v26, 16, v129
	v_and_b32_e32 v27, 0xffff0000, v129
	v_lshlrev_b32_e32 v28, 16, v130
	v_and_b32_e32 v29, 0xffff0000, v130
	v_lshlrev_b32_e32 v30, 16, v131
	v_and_b32_e32 v31, 0xffff0000, v131
	v_cmp_lt_u32_e32 vcc, 4, v76
	s_and_saveexec_b64 s[4:5], vcc
	s_cbranch_execz .Lgs_nosd
	global_store_dwordx4 v61, v[24:27], s[16:17]
	global_store_dwordx4 v61, v[28:31], s[16:17] offset:16
.Lgs_nosd:
	s_or_b64 exec, exec, s[4:5]
	v_pk_fma_f32 v[32:33], v[0:1], v[84:85], 0 op_sel_hi:[1,1,0]
	v_pk_fma_f32 v[34:35], v[2:3], v[86:87], 0 op_sel_hi:[1,1,0]
	v_pk_fma_f32 v[36:37], v[4:5], v[88:89], 0 op_sel_hi:[1,1,0]
	v_pk_fma_f32 v[38:39], v[6:7], v[90:91], 0 op_sel_hi:[1,1,0]
	v_pk_fma_f32 v[32:33], v[8:9], v[92:93], v[32:33]
	v_pk_fma_f32 v[34:35], v[10:11], v[94:95], v[34:35]
	v_pk_fma_f32 v[36:37], v[12:13], v[96:97], v[36:37]
	v_pk_fma_f32 v[38:39], v[14:15], v[98:99], v[38:39]
	v_pk_fma_f32 v[32:33], v[16:17], v[100:101], v[32:33]
	v_pk_fma_f32 v[34:35], v[18:19], v[102:103], v[34:35]
	v_pk_fma_f32 v[36:37], v[20:21], v[104:105], v[36:37]
	v_pk_fma_f32 v[38:39], v[22:23], v[106:107], v[38:39]
	v_pk_fma_f32 v[32:33], v[24:25], v[108:109], v[32:33]
	v_pk_fma_f32 v[34:35], v[26:27], v[110:111], v[34:35]
	v_pk_fma_f32 v[36:37], v[28:29], v[112:113], v[36:37]
	v_pk_fma_f32 v[38:39], v[30:31], v[114:115], v[38:39]
	v_mul_f32_e32 v40, 0xbfb8aa3b, v32
	v_mul_f32_e32 v41, 0xbfb8aa3b, v33
	v_mul_f32_e32 v42, 0xbfb8aa3b, v34
	v_mul_f32_e32 v43, 0xbfb8aa3b, v35
	v_mul_f32_e32 v44, 0xbfb8aa3b, v36
	v_mul_f32_e32 v45, 0xbfb8aa3b, v37
	v_mul_f32_e32 v46, 0xbfb8aa3b, v38
	v_mul_f32_e32 v47, 0xbfb8aa3b, v39
	v_exp_f32_e32 v40, v40
	v_exp_f32_e32 v41, v41
	v_exp_f32_e32 v42, v42
	v_exp_f32_e32 v43, v43
	v_exp_f32_e32 v44, v44
	v_exp_f32_e32 v45, v45
	v_exp_f32_e32 v46, v46
	v_exp_f32_e32 v47, v47
	v_add_f32_e32 v40, 1.0, v40
	v_add_f32_e32 v41, 1.0, v41
	v_add_f32_e32 v42, 1.0, v42
	v_add_f32_e32 v43, 1.0, v43
	v_add_f32_e32 v44, 1.0, v44
	v_add_f32_e32 v45, 1.0, v45
	v_add_f32_e32 v46, 1.0, v46
	v_add_f32_e32 v47, 1.0, v47
	v_rcp_f32_e32 v40, v40
	v_rcp_f32_e32 v41, v41
	v_rcp_f32_e32 v42, v42
	v_rcp_f32_e32 v43, v43
	v_rcp_f32_e32 v44, v44
	v_rcp_f32_e32 v45, v45
	v_rcp_f32_e32 v46, v46
	v_rcp_f32_e32 v47, v47
	v_pk_mul_f32 v[32:33], v[32:33], v[40:41]
	v_pk_mul_f32 v[34:35], v[34:35], v[42:43]
	v_pk_mul_f32 v[36:37], v[36:37], v[44:45]
	v_pk_mul_f32 v[38:39], v[38:39], v[46:47]
	ds_write_b128 v53, v[32:35]
	ds_write_b128 v53, v[36:39] offset:16
.Lgs_done:
.LBB0_1070:
	s_or_b64 exec, exec, s[0:1]
	v_and_b32_e32 v1, 63, v64
	v_ashrrev_i32_e32 v2, 6, v64
	v_lshlrev_b32_e32 v0, 2, v1
	v_lshl_or_b32 v3, v2, 9, v0
	v_add_u32_e32 v5, 0, v3
	s_waitcnt lgkmcnt(0)
	s_barrier
	ds_read2st64_b32 v[6:7], v5 offset1:1
	ds_read2st64_b32 v[8:9], v5 offset0:16 offset1:17
	v_and_b32_e32 v3, 64, v182
	v_add_u32_e32 v3, 64, v3
	v_xor_b32_e32 v4, 1, v182
	s_waitcnt lgkmcnt(1)
	v_pk_mul_f32 v[10:11], v[6:7], v[6:7]
	v_cmp_lt_i32_e32 vcc, v4, v3
	s_waitcnt lgkmcnt(0)
	v_pk_mul_f32 v[12:13], v[8:9], v[8:9]
	v_mov_b32_e32 v15, v10
	v_cndmask_b32_e32 v4, v182, v4, vcc
	v_mov_b32_e32 v14, v12
	v_mov_b32_e32 v10, v13
	v_lshlrev_b32_e32 v41, 2, v4
	v_pk_add_f32 v[10:11], v[14:15], v[10:11]
	ds_bpermute_b32 v13, v41, v11
	ds_bpermute_b32 v12, v41, v10
	v_xor_b32_e32 v4, 2, v182
	v_cmp_lt_i32_e32 vcc, v4, v3
	s_mov_b32 s0, 0x358637bd
	s_waitcnt lgkmcnt(0)
	v_pk_add_f32 v[10:11], v[10:11], v[12:13]
	v_cndmask_b32_e32 v4, v182, v4, vcc
	v_lshlrev_b32_e32 v43, 2, v4
	ds_bpermute_b32 v13, v43, v11
	ds_bpermute_b32 v12, v43, v10
	v_xor_b32_e32 v4, 4, v182
	v_cmp_lt_i32_e32 vcc, v4, v3
	s_waitcnt lgkmcnt(0)
	v_pk_add_f32 v[10:11], v[10:11], v[12:13]
	v_cndmask_b32_e32 v4, v182, v4, vcc
	v_lshlrev_b32_e32 v44, 2, v4
	ds_bpermute_b32 v13, v44, v11
	ds_bpermute_b32 v12, v44, v10
	v_xor_b32_e32 v4, 8, v182
	v_cmp_lt_i32_e32 vcc, v4, v3
	s_waitcnt lgkmcnt(0)
	v_pk_add_f32 v[10:11], v[10:11], v[12:13]
	v_cndmask_b32_e32 v4, v182, v4, vcc
	v_lshlrev_b32_e32 v45, 2, v4
	ds_bpermute_b32 v13, v45, v11
	ds_bpermute_b32 v12, v45, v10
	v_xor_b32_e32 v4, 16, v182
	v_cmp_lt_i32_e32 vcc, v4, v3
	s_waitcnt lgkmcnt(0)
	v_pk_add_f32 v[10:11], v[10:11], v[12:13]
	v_cndmask_b32_e32 v4, v182, v4, vcc
	v_lshlrev_b32_e32 v46, 2, v4
	ds_bpermute_b32 v13, v46, v11
	ds_bpermute_b32 v12, v46, v10
	v_xor_b32_e32 v4, 32, v182
	v_cmp_lt_i32_e32 vcc, v4, v3
	s_waitcnt lgkmcnt(0)
	v_pk_add_f32 v[10:11], v[10:11], v[12:13]
	v_cndmask_b32_e32 v3, v182, v4, vcc
	v_lshlrev_b32_e32 v47, 2, v3
	ds_bpermute_b32 v13, v47, v11
	ds_bpermute_b32 v12, v47, v10
	s_waitcnt lgkmcnt(0)
	v_pk_add_f32 v[10:11], v[10:11], v[12:13]
	s_nop 0
	v_pk_add_f32 v[10:11], v[10:11], s[0:1] op_sel_hi:[1,0]
	s_nop 0
	v_mul_f32_e32 v3, 0x4b800000, v11
	v_cmp_gt_f32_e32 vcc, s80, v11
	s_nop 1
	v_cndmask_b32_e32 v3, v11, v3, vcc
	v_rsq_f32_e32 v3, v3
	s_nop 0
	v_mul_f32_e32 v4, 0x45800000, v3
	v_cndmask_b32_e32 v3, v3, v4, vcc
	v_mul_f32_e32 v4, 0x4b800000, v10
	v_cmp_gt_f32_e32 vcc, s80, v10
	v_mul_f32_e32 v3, 0x3db504f3, v3
	v_mul_f32_e32 v6, v6, v3
	v_cndmask_b32_e32 v4, v10, v4, vcc
	v_rsq_f32_e32 v4, v4
	v_mul_f32_e32 v3, v7, v3
	ds_write2st64_b32 v5, v6, v3 offset1:1
	v_mul_f32_e32 v3, 0x45800000, v4
	v_cndmask_b32_e32 v3, v4, v3, vcc
	v_mul_f32_e32 v4, v8, v3
	v_mul_f32_e32 v3, v9, v3
	ds_write2st64_b32 v5, v4, v3 offset0:16 offset1:17
	v_cmp_gt_i32_e32 vcc, 8, v64
	v_lshl_add_u32 v3, v64, 2, 0
	s_and_saveexec_b64 s[2:3], vcc
	s_cbranch_execz .LBB0_1076
	v_ashrrev_i32_e32 v65, 31, v64
	v_lshl_add_u64 v[6:7], s[36:37], 0, v[64:65]
	v_mov_b64_e32 v[8:9], s[12:13]
	v_mad_u64_u32 v[8:9], s[0:1], v6, s86, v[8:9]
	v_mad_i32_i24 v9, v7, s86, v9
	s_lshl_b32 s66, s6, 1
	v_lshl_add_u64 v[6:7], v[8:9], 0, s[66:67]
	v_add_co_u32_e32 v6, vcc, 0x1000, v6
	v_readlane_b32 s0, v244, 23
	s_nop 0
	v_addc_co_u32_e32 v7, vcc, 0, v7, vcc
	flat_load_ushort v4, v[6:7] offset:2048
	s_or_b32 s66, s6, s0
	flat_load_ushort v6, v[6:7] offset:2064
	s_lshl_b64 s[0:1], s[66:67], 2
	s_add_u32 s4, s75, s0
	s_addc_u32 s5, s82, s1
	s_add_u32 s0, s83, s0
	s_addc_u32 s1, s18, s1
	s_waitcnt vmcnt(0) lgkmcnt(0)
	v_lshlrev_b32_e32 v4, 16, v4
	v_mul_f32_e32 v4, 0xbfb8aa3b, v4
	v_exp_f32_e32 v4, v4
	v_lshlrev_b32_e32 v8, 16, v6
	v_mov_b64_e32 v[6:7], s[4:5]
	v_add_f32_e32 v4, 1.0, v4
	v_rcp_f32_e32 v4, v4
	ds_write_b32 v3, v4 offset:20480
	flat_load_dword v4, v[6:7]
	v_mov_b64_e32 v[6:7], s[0:1]
	flat_load_dword v6, v[6:7]
	s_mov_b32 s0, 0x3cf5c28f
	s_waitcnt vmcnt(0) lgkmcnt(0)
	v_add_f32_e32 v6, v6, v8
	v_min_f32_e32 v7, 0x41a00000, v6
	v_mul_f32_e32 v7, 0x3fb8aa3b, v7
	v_exp_f32_e32 v8, v7
	s_nop 0
	v_cmp_ngt_f32_e32 vcc, s0, v8
	s_and_saveexec_b64 s[0:1], vcc
	s_xor_b64 s[4:5], exec, s[0:1]
	s_cbranch_execz .LBB0_1073
	v_add_f32_e32 v7, 1.0, v8
	v_cmp_gt_f32_e32 vcc, s80, v7
	s_mov_b32 s0, 0x3f317217
	s_nop 0
	v_cndmask_b32_e64 v8, 0, 32, vcc
	v_ldexp_f32 v7, v7, v8
	v_log_f32_e32 v7, v7
	s_nop 0
	v_mul_f32_e32 v8, 0x3f317217, v7
	v_fma_f32 v8, v7, s0, -v8
	v_fmac_f32_e32 v8, 0x3377d1cf, v7
	s_mov_b32 s0, 0x7f800000
	v_fmac_f32_e32 v8, 0x3f317217, v7
	v_cmp_lt_f32_e64 s[0:1], |v7|, s0
	s_nop 1
	v_cndmask_b32_e64 v7, v7, v8, s[0:1]
	v_cndmask_b32_e32 v8, 0, v183, vcc
	v_sub_f32_e32 v7, v7, v8

.LBB0_1076:
	s_or_b64 exec, exec, s[2:3]
	s_add_i32 s7, s7, s24
	s_lshl_b32 s0, s7, 3
	v_ashrrev_i32_e32 v6, 2, v64
	s_or_b32 s0, s0, s6
	v_and_b32_e32 v48, 0xffffffe0, v6
	s_ashr_i32 s1, s0, 31
	v_ashrrev_i32_e32 v49, 31, v48
	s_lshl_b64 s[0:1], s[0:1], 14
	v_lshlrev_b64 v[6:7], 7, v[48:49]
	v_and_b32_e32 v4, 0x7f, v64
	v_lshl_add_u64 v[6:7], v[6:7], 0, s[0:1]
	v_lshl_add_u64 v[8:9], v[6:7], 2, s[28:29]
	v_lshlrev_b32_e32 v144, 2, v4
	v_lshl_add_u64 v[8:9], v[8:9], 0, v[144:145]
	s_movk_i32 s0, 0x1000
	v_add_co_u32_e32 v10, vcc, s0, v8
	s_waitcnt vmcnt(0)
	v_mov_b32_e32 v38, v190
	v_mov_b32_e32 v39, v191
	v_mov_b32_e32 v36, v192
	v_mov_b32_e32 v37, v193
	v_mov_b32_e32 v34, v194
	v_mov_b32_e32 v35, v195
	v_mov_b32_e32 v32, v196
	v_mov_b32_e32 v33, v197
	v_addc_co_u32_e32 v11, vcc, 0, v9, vcc
	v_mov_b32_e32 v30, v198
	v_mov_b32_e32 v31, v199
	v_mov_b32_e32 v28, v200
	v_mov_b32_e32 v29, v201
	v_mov_b32_e32 v26, v202
	v_mov_b32_e32 v27, v203
	v_mov_b32_e32 v24, v204
	v_mov_b32_e32 v25, v205
	v_add_co_u32_e32 v10, vcc, s87, v8
	s_movk_i32 s0, 0x80
	s_nop 0
	v_addc_co_u32_e32 v11, vcc, 0, v9, vcc
	v_add_co_u32_e32 v50, vcc, s71, v8
	v_mov_b32_e32 v22, v206
	v_mov_b32_e32 v23, v207
	v_mov_b32_e32 v20, v208
	v_mov_b32_e32 v21, v209
	v_mov_b32_e32 v18, v210
	v_mov_b32_e32 v19, v211
	v_mov_b32_e32 v16, v212
	v_mov_b32_e32 v17, v213
	v_addc_co_u32_e32 v51, vcc, 0, v9, vcc
	v_mov_b32_e32 v14, v214
	v_mov_b32_e32 v15, v215
	v_mov_b32_e32 v12, v216
	v_mov_b32_e32 v13, v217
	v_mov_b32_e32 v10, v218
	v_mov_b32_e32 v11, v219
	v_mov_b32_e32 v8, v220
	v_mov_b32_e32 v9, v221
	v_cmp_gt_u32_e32 vcc, s0, v64
	s_add_i32 s0, 0, 0x2000
	s_mov_b32 s2, 0
	v_lshl_add_u32 v48, v48, 2, 0
	v_add_u32_e32 v49, 0, v144
	v_add_u32_e32 v50, s0, v144
	s_add_i32 s3, 0, 0x5000
	s_waitcnt lgkmcnt(0)
	s_barrier
	s_branch .LBB0_1078
